# attention K tile LDS swizzle with 4 row bits (conflict-free ds_read_b128 groups), on top of speculative-softmax variant
# baseline (speedup 1.0000x reference)
; #define DMA_TILE(t, buf) do { const char* kt = (const char*)Kh + (size_t)(t) * (64 * 2048 * 2); const char* vt = (const char*)Vh + (size_t)(t) * (64 * 2048 * 2); \
;     _Pragma("unroll") for (int i = 0; i < 8; ++i) __builtin_amdgcn_global_load_lds((const unsigned*)((wid < 4 ? kt : vt) + src_off(wid * 8 + i, lane)), (LAS unsigned*)(lds + (buf) * 65536 + (wid * 8 + i) * 1024), 16, 0, 0); } while (0)
; __device__ __forceinline__ unsigned src_off(int p, int L) {
;     const int reg = p >> 4, pp = p & 15; const int o = pp * 1024 + L * 16;
;     if (reg < 2) { const int r = o >> 8, cc = (o >> 4) & 15; const int c = cc ^ (r & 7); return (unsigned)(r * LDK + reg * 128 + c * 8) * 2u; }
;     const int st = o >> 9, w = o & 511; const int kk = ((st >> 2) << 3) | (w >> 6); const int c = ((st & 3) << 5) | ((w & 63) >> 1);
;     const int k = (kk & ~0xC) | ((kk & 4) << 1) | ((kk & 8) >> 1);
;     return (unsigned)(k * LDK + (reg - 2) * 128 + c) * 2u;
; }
; __device__ __forceinline__ void dattn_unit(const bf16* __restrict__ Qb, const bf16* __restrict__ Kh, const bf16* __restrict__ Vh, int nq, int kv_lo, int kv_hi, int NT, ...
;     ...
;   DMA_TILE(0, 0);
.LBB0_907:
	s_cmp_lt_i32 s83, 4
	s_cselect_b32 s15, s1, s7
	s_cselect_b32 s14, s0, s6
	s_cselect_b32 s32, 0x80, 0
	s_add_i32 s24, s19, 0
	s_mov_b32 m0, s24
	s_or_b32 s0, s19, 0x400
	global_load_lds_dwordx4 v2, s[14:15]
	s_and_b32 s0, s0, 0x2400
	v_or_b32_e32 v2, s0, v12
	v_cndmask_b32_e64 v13, 0, 1, s[8:9]
	v_cmp_ne_u32_e64 s[0:1], 1, v13
	v_lshrrev_b32_e32 v13, 4, v2
	s_mov_b64 s[6:7], -1
	s_andn2_b64 vcc, exec, s[8:9]
	v_and_b32_e32 v13, 0x60, v13
	s_cbranch_vccnz .LBB0_909
	s_lshr_b32 s6, s19, 8
	v_or_b32_e32 v14, s6, v5
	v_and_or_b32 v14, v14, 35, v6
	v_or3_b32 v15, v7, v13, s18
	v_lshlrev_b32_e32 v14, 12, v14
	v_lshl_add_u32 v16, v15, 1, v14
	s_mov_b64 s[6:7], 0

.LBB0_915:
	s_add_i32 m0, s24, 0x800
	s_or_b32 s6, s19, 0xc00
	v_xor_b32_e32 v250, s32, v2
	global_load_lds_dwordx4 v250, s[14:15]
	s_and_b32 s6, s6, 0x2c00
	v_or_b32_e32 v2, s6, v12
	v_lshrrev_b32_e32 v18, 4, v2
	s_mov_b64 s[6:7], -1
	s_and_b64 vcc, exec, s[0:1]
	v_and_b32_e32 v18, 0x60, v18
	s_cbranch_vccnz .LBB0_917
	s_lshr_b32 s6, s19, 8
	v_or_b32_e32 v19, s6, v5
	v_and_or_b32 v19, v19, 35, v6
	v_or3_b32 v20, v7, v18, s18
	v_lshlrev_b32_e32 v19, 12, v19
	v_lshlrev_b32_e32 v20, 1, v20
	v_add3_u32 v21, v20, v19, s91
	s_mov_b64 s[6:7], 0

.LBB0_919:
	s_add_i32 m0, s24, 0xc00
	s_or_b32 s8, s19, 0x1000
	v_xor_b32_e32 v250, s32, v21
	global_load_lds_dwordx4 v250, s[14:15]
	s_and_b64 vcc, exec, s[0:1]
	s_mov_b64 s[6:7], -1
	s_cbranch_vccnz .LBB0_921
	s_lshr_b32 s6, s8, 8
	v_or_b32_e32 v2, s6, v5
	v_and_or_b32 v2, v2, 51, v6
	v_lshlrev_b32_e32 v21, 1, v8
	v_lshl_add_u32 v2, v2, 12, v21
	s_mov_b64 s[6:7], 0

.LBB0_931:
	s_add_i32 m0, s24, 0x1800
	s_or_b32 s6, s19, 0x1c00
	v_xor_b32_e32 v250, s32, v2
	global_load_lds_dwordx4 v250, s[14:15]
	s_and_b32 s7, s6, 0x3c00
	v_or_b32_e32 v28, s7, v12
	s_and_b64 vcc, exec, s[0:1]
	s_mov_b64 s[0:1], -1
	s_cbranch_vccnz .LBB0_933
	s_lshr_b32 s0, s6, 8
	v_lshrrev_b32_e32 v29, 4, v28
	v_or_b32_e32 v2, s0, v5
	v_and_b32_e32 v29, 0x60, v29
	v_and_or_b32 v2, v2, 51, v6
	v_or3_b32 v29, v7, v29, s18
	v_lshlrev_b32_e32 v2, 12, v2
	v_lshlrev_b32_e32 v29, 1, v29
	v_add3_u32 v2, v29, v2, s91
	s_mov_b64 s[0:1], 0

; __device__ __forceinline__ int v_rd_base(int lane) { return ((lane & 3) << 3) | (((lane >> 2) & 3) << 6) | (((lane >> 4) & 1) << 5) | (((lane >> 5) & 1) << 8); }
; #define DMA_TILE(t, buf) do { const char* kt = (const char*)Kh + (size_t)(t) * (64 * 2048 * 2); const char* vt = (const char*)Vh + (size_t)(t) * (64 * 2048 * 2); \
;     _Pragma("unroll") for (int i = 0; i < 8; ++i) __builtin_amdgcn_global_load_lds((const unsigned*)((wid < 4 ? kt : vt) + src_off(wid * 8 + i, lane)), (LAS unsigned*)(lds + (buf) * 65536 + (wid * 8 + i) * 1024), 16, 0, 0); } while (0)
; __device__ __forceinline__ void dattn_unit(const bf16* __restrict__ Qb, const bf16* __restrict__ Kh, const bf16* __restrict__ Vh, int nq, int kv_lo, int kv_hi, int NT, ...
;     ...
;   DMA_TILE(0, 0);
;   for (int t = 0; t < NT; ++t) {
;     asm volatile("s_waitcnt vmcnt(0)" ::: "memory");
;     __builtin_amdgcn_s_barrier();
;     if (t + 1 < NT) DMA_TILE(t + 1, (t + 1) & 1);
;     const int rem = kvalid - 64 * t;
;     if (active && rem > 0) {
;       const bf16* Ks = (const bf16*)(lds + (t & 1) * 65536 + br * 16384);
;       const int vb = (int)(uintptr_t)(lds + (t & 1) * 65536 + 32768) + v_rd_base(lane);
;       f32x16 p0, p1; float mn, al; bf16x8 pa0, pa1, pa2, pa3;
;       p0 = f32x16{}; p1 = f32x16{};
; #pragma unroll
;       for (int d0 = 0; d0 < 8; ++d0) { const int cb = (d0 * 16 + hi * 8) * 2;
;         const bf16x8 b0 = *reinterpret_cast<const bf16x8*>((const char*)Ks + KSWZ(r32, cb));
;         const bf16x8 b1 = *reinterpret_cast<const bf16x8*>((const char*)Ks + KSWZ(32 + r32, cb));
.LBB0_935:
	s_and_b32 s0, s21, 0x3fffffc0
	s_lshl_b32 s0, s0, 2
	s_add_i32 s0, s0, 0
	s_add_i32 s6, s0, 0x20000
	s_cmp_lt_u32 s2, 2
	s_cselect_b32 s25, s17, s16
	s_cmp_lt_u32 s80, s20
	s_cselect_b64 s[12:13], -1, 0
	s_add_i32 m0, s24, 0x1c00
	v_lshlrev_b32_e32 v28, 1, v233
	v_xor_b32_e32 v250, s32, v2
	global_load_lds_dwordx4 v250, s[14:15]
	v_and_b32_e32 v28, 32, v28
	s_movk_i32 s16, 0xc0
	v_and_or_b32 v12, v12, s16, v28
	v_and_b32_e32 v9, 0x100, v9
	s_lshr_b32 s7, s19, 8
	v_or3_b32 v235, v12, v9, v7
	v_or_b32_e32 v12, s7, v5
	v_and_or_b32 v12, v12, 35, v6
	v_lshlrev_b32_e32 v12, 12, v12
	v_lshlrev_b32_e32 v8, 1, v8
	v_lshl_or_b32 v10, v10, 4, v11
	v_or3_b32 v11, v7, v13, s18
	s_lshr_b32 s7, s8, 8
	v_add_u32_e32 v28, v12, v8
	v_lshl_add_u32 v11, v11, 1, v12
	v_lshl_or_b32 v13, v14, 4, v15
	v_or_b32_e32 v12, 0x4000, v12
	v_lshl_or_b32 v15, v16, 4, v17
	v_or3_b32 v16, v7, v18, s18
	v_or_b32_e32 v17, s7, v5
	s_lshr_b32 s7, s9, 8
	v_add_u32_e32 v14, v12, v8
	v_lshl_add_u32 v12, v16, 1, v12
	v_lshl_or_b32 v16, v19, 4, v20
	v_or_b32_e32 v19, s7, v5
	s_lshr_b32 s7, s27, 8
	v_lshlrev_b32_e32 v4, 4, v4
	v_or_b32_e32 v5, s7, v5
	s_movk_i32 s7, 0x70
	v_and_b32_e32 v9, 0x70, v4
	v_bitop3_b32 v238, v0, v4, s7 bitop3:0x78
	s_movk_i32 s7, 0x60
	v_and_or_b32 v19, v19, 51, v6
	v_and_or_b32 v5, v5, 51, v6
	v_bitop3_b32 v241, v0, v9, s7 bitop3:0x36
	s_movk_i32 s7, 0x80
	v_and_or_b32 v17, v17, 51, v6
	v_or3_b32 v7, v7, v23, s18
	v_lshlrev_b32_e32 v19, 12, v19
	v_lshlrev_b32_e32 v5, 12, v5
	v_bitop3_b32 v242, v0, v9, s7 bitop3:0x36
	s_movk_i32 s7, 0xa0
	v_lshl_add_u32 v17, v17, 12, v8
	v_lshl_or_b32 v18, v21, 4, v22
	v_lshl_add_u32 v19, v7, 1, v19
	v_lshl_or_b32 v20, v24, 4, v25
	v_add3_u32 v21, v8, v5, s91
	v_lshl_or_b32 v22, v26, 4, v27
	v_bitop3_b32 v243, v0, v9, s7 bitop3:0x36
	s_movk_i32 s7, 0xe0
	v_bitop3_b32 v239, v0, v9, 32 bitop3:0x36
	v_bitop3_b32 v240, v0, v9, 64 bitop3:0x36
	v_bitop3_b32 v244, v0, v9, s16 bitop3:0x36
	v_bitop3_b32 v245, v0, v9, s7 bitop3:0x36
	v_add_u32_e32 v237, s6, v0
	v_cndmask_b32_e64 v0, v28, v10, s[4:5]
	v_cndmask_b32_e64 v4, v11, v13, s[4:5]
	v_cndmask_b32_e64 v6, v14, v15, s[4:5]
	v_cndmask_b32_e64 v8, v12, v16, s[4:5]
	v_cndmask_b32_e64 v10, v17, v18, s[4:5]
	v_cndmask_b32_e64 v12, v19, v20, s[4:5]
	v_cndmask_b32_e64 v14, v21, v22, s[4:5]
	v_mov_b32_e32 v15, v1
	s_mov_b64 s[4:5], 0x40000
	v_mov_b32_e32 v3, v1
	v_mov_b32_e32 v5, v1
	v_mov_b32_e32 v7, v1
	v_mov_b32_e32 v9, v1
	v_mov_b32_e32 v11, v1
	v_mov_b32_e32 v13, v1
	v_add_u32_e32 v218, 0x40000, v14
	v_mov_b32_e32 v14, v1
	v_add_u32_e32 v212, 0x40000, v0
	v_add_u32_e32 v213, 0x40000, v4
	v_add_u32_e32 v214, 0x40000, v6
	v_add_u32_e32 v215, 0x40000, v8
	v_add_u32_e32 v216, 0x40000, v10
	v_add_u32_e32 v217, 0x40000, v12
	v_add_u32_e32 v219, 0x40000, v2
	v_xor_b32_e32 v214, s32, v214
	v_xor_b32_e32 v215, s32, v215
	v_xor_b32_e32 v218, s32, v218
	v_xor_b32_e32 v219, s32, v219
	v_mov_b32_e32 v0, v1
	v_mov_b32_e32 v2, v1
	v_mov_b32_e32 v4, v1
	v_mov_b32_e32 v6, v1
	v_mov_b32_e32 v8, v1
	v_mov_b32_e32 v10, v1
	v_mov_b32_e32 v12, v1
	v_mov_b64_e32 v[128:129], v[14:15]
	v_mov_b64_e32 v[112:113], v[14:15]
	v_mov_b64_e32 v[96:97], v[14:15]
	v_mov_b64_e32 v[80:81], v[14:15]
	v_mov_b64_e32 v[64:65], v[14:15]
	v_mov_b64_e32 v[48:49], v[14:15]
	v_mov_b64_e32 v[32:33], v[14:15]
	v_mov_b64_e32 v[126:127], v[12:13]
	v_mov_b64_e32 v[124:125], v[10:11]
	v_mov_b64_e32 v[122:123], v[8:9]
	v_mov_b64_e32 v[120:121], v[6:7]
	v_mov_b64_e32 v[118:119], v[4:5]
	v_mov_b64_e32 v[116:117], v[2:3]
	v_mov_b64_e32 v[114:115], v[0:1]
	v_mov_b64_e32 v[110:111], v[12:13]
	v_mov_b64_e32 v[108:109], v[10:11]
	v_mov_b64_e32 v[106:107], v[8:9]
	v_mov_b64_e32 v[104:105], v[6:7]
	v_mov_b64_e32 v[102:103], v[4:5]
	v_mov_b64_e32 v[100:101], v[2:3]
	v_mov_b64_e32 v[98:99], v[0:1]
	v_mov_b64_e32 v[94:95], v[12:13]
	v_mov_b64_e32 v[92:93], v[10:11]
	v_mov_b64_e32 v[90:91], v[8:9]
	v_mov_b64_e32 v[88:89], v[6:7]
	v_mov_b64_e32 v[86:87], v[4:5]
	v_mov_b64_e32 v[84:85], v[2:3]
	v_mov_b64_e32 v[82:83], v[0:1]
	v_mov_b64_e32 v[78:79], v[12:13]
	v_mov_b64_e32 v[76:77], v[10:11]
	v_mov_b64_e32 v[74:75], v[8:9]
	v_mov_b64_e32 v[72:73], v[6:7]
	v_mov_b64_e32 v[70:71], v[4:5]
	v_mov_b64_e32 v[68:69], v[2:3]
	v_mov_b64_e32 v[66:67], v[0:1]
	v_mov_b64_e32 v[62:63], v[12:13]
	v_mov_b64_e32 v[60:61], v[10:11]
	v_mov_b64_e32 v[58:59], v[8:9]
	v_mov_b64_e32 v[56:57], v[6:7]
	v_mov_b64_e32 v[54:55], v[4:5]
	v_mov_b64_e32 v[52:53], v[2:3]
	v_mov_b64_e32 v[50:51], v[0:1]
	v_mov_b64_e32 v[46:47], v[12:13]
	v_mov_b64_e32 v[44:45], v[10:11]
	v_mov_b64_e32 v[42:43], v[8:9]
	v_mov_b64_e32 v[40:41], v[6:7]
	v_mov_b64_e32 v[38:39], v[4:5]
	v_mov_b64_e32 v[36:37], v[2:3]
	v_mov_b64_e32 v[34:35], v[0:1]
	v_mov_b64_e32 v[30:31], v[12:13]
	v_mov_b64_e32 v[28:29], v[10:11]
	v_mov_b64_e32 v[26:27], v[8:9]
	v_mov_b64_e32 v[24:25], v[6:7]
	v_mov_b64_e32 v[22:23], v[4:5]
	v_mov_b64_e32 v[20:21], v[2:3]
	v_mov_b64_e32 v[18:19], v[0:1]
	v_mov_b64_e32 v[16:17], v[14:15]
	s_lshl_b32 s26, s22, 14
	v_lshlrev_b32_e32 v236, 8, v230
	v_cmp_gt_u32_e64 s[0:1], 32, v233
	v_lshl_add_u32 v234, v230, 2, s6
	v_lshlrev_b32_e32 v232, 2, v231
	s_mov_b32 s27, 0
	v_mov_b32_e32 v247, 0
	v_mov_b32_e32 v246, 0xf149f2ca
	v_mov_b64_e32 v[14:15], v[12:13]
	v_mov_b64_e32 v[12:13], v[10:11]
	v_mov_b64_e32 v[10:11], v[8:9]
	v_mov_b64_e32 v[8:9], v[6:7]
	v_mov_b64_e32 v[6:7], v[4:5]
	v_mov_b64_e32 v[4:5], v[2:3]
	v_mov_b64_e32 v[2:3], v[0:1]
	s_mov_b32 s28, 0
	v_and_b32_e32 v250, 8, v230
	v_lshlrev_b32_e32 v250, 4, v250
	v_xor_b32_e32 v238, v250, v238
	v_xor_b32_e32 v239, v250, v239
	v_xor_b32_e32 v240, v250, v240
	v_xor_b32_e32 v241, v250, v241
	v_xor_b32_e32 v242, v250, v242
	v_xor_b32_e32 v243, v250, v243
	v_xor_b32_e32 v244, v250, v244
	v_xor_b32_e32 v245, v250, v245
	s_waitcnt vmcnt(0)
	s_branch .LBB0_939
